# hgrn stage 2: loads prefetched six chunks ahead (was four), one guarded 6-chunk loop body instead of peeled prologue + loop
# speedup vs baseline: 1.0204x; 1.0042x over previous
.LBB0_550:
	v_readlane_b32 s6, v250, 2
	s_nop 3
	s_cmp_lg_u32 s6, 0
	s_cbranch_scc0 .Ls2_orig
	s_lshr_b32 s7, s24, 4
	s_and_b32 s8, s24, 3
	s_lshr_b32 s9, s24, 2
	s_lshl_b32 s9, s9, 6
	s_mul_i32 s23, s7, 12
	s_add_u32 s26, s23, 8
	s_lshl_b32 s26, s26, 20
	s_lshl_b32 s27, s9, 14
	s_add_u32 s26, s26, s27
	s_add_u32 s10, s38, s26
	s_addc_u32 s11, s39, 0
	s_lshl_b32 s26, s7, 23
	s_lshl_b32 s30, s9, 15
	s_add_u32 s26, s26, s30
	s_add_u32 s12, s38, s26
	s_addc_u32 s13, s39, 0
	s_add_u32 s26, s23, 12
	s_lshl_b32 s26, s26, 20
	s_add_u32 s26, s26, s27
	s_add_u32 s14, s38, s26
	s_addc_u32 s15, s39, 0
	v_readlane_b32 s16, v248, 29
	v_readlane_b32 s17, v248, 30
	s_lshl_b32 s26, s9, 9
	s_nop 1
	s_add_u32 s16, s16, s26
	s_addc_u32 s17, s17, 0
	v_readlane_b32 s18, v250, 10
	v_readlane_b32 s19, v250, 11
	s_lshl_b32 s26, s7, 23
	s_lshr_b32 s27, s24, 2
	s_and_b32 s27, s27, 3
	s_lshl_b32 s27, s27, 8
	s_add_u32 s26, s26, s27
	s_lshl_b32 s27, s8, 6
	s_add_u32 s26, s26, s27
	s_add_u32 s18, s18, s26
	s_addc_u32 s19, s19, 0
	v_and_b32_e32 v228, 63, v216
	v_lshrrev_b32_e32 v229, 6, v216
	v_and_b32_e32 v230, 15, v216
	v_bfe_u32 v231, v216, 4, 2
	v_lshrrev_b32_e32 v232, 1, v229
	v_and_b32_e32 v233, 1, v229
	v_lshlrev_b32_e32 v8, 4, v216
	v_add_u32_e32 v9, 0x2000, v8
	v_lshlrev_b32_e32 v10, 12, v229
	v_lshl_add_u32 v10, v228, 3, v10
	s_lshl_b32 s26, s8, 10
	v_add_u32_e32 v10, s26, v10
	v_lshlrev_b32_e32 v11, 12, v232
	v_lshl_add_u32 v11, v233, 9, v11
	v_lshl_add_u32 v11, v228, 3, v11
	v_add_u32_e32 v11, s26, v11
	v_lshlrev_b32_e32 v12, 6, v229
	v_lshl_add_u32 v12, v231, 4, v12
	v_lshlrev_b32_e32 v234, 2, v232
	v_add_u32_e32 v234, v234, v231
	v_lshlrev_b32_e32 v13, 13, v234
	v_lshl_add_u32 v235, v233, 4, v230
	v_lshl_add_u32 v13, v235, 1, v13
	v_add_u32_e32 v14, 0x1000, v13
	v_lshrrev_b32_e32 v234, 4, v216
	v_mul_u32_u24_e32 v15, 0x110, v234
	v_lshl_add_u32 v15, v230, 4, v15
	v_mul_u32_u24_e32 v16, 0x110, v230
	v_lshl_add_u32 v234, v229, 2, v231
	v_lshl_add_u32 v16, v234, 3, v16
	v_add_u32_e32 v16, 0x4400, v16
	v_lshl_add_u32 v234, v232, 4, v230
	v_mul_u32_u24_e32 v17, 0x110, v234
	v_lshl_add_u32 v17, v231, 4, v17
	v_mul_u32_u24_e32 v18, 0x110, v235
	v_lshl_add_u32 v18, v231, 4, v18
	v_add_u32_e32 v18, 0x4400, v18
	v_mov_b32_e32 v0, 0
	v_mov_b32_e32 v1, 0
	v_mov_b32_e32 v2, 0
	v_mov_b32_e32 v3, 0
	v_mov_b32_e32 v4, 0
	v_mov_b32_e32 v5, 0
	v_mov_b32_e32 v6, 0
	v_mov_b32_e32 v7, 0
	global_load_dwordx4 v[20:23], v8, s[10:11]
	global_load_dwordx4 v[24:27], v9, s[10:11]
	global_load_dwordx2 v[28:29], v10, s[12:13]
	global_load_dwordx2 v[30:31], v10, s[12:13] offset:512
	global_load_dwordx2 v[32:33], v11, s[14:15]
	global_load_dwordx4 v[34:37], v12, s[16:17]
	s_add_u32 s10, s10, 0x4000
	s_addc_u32 s11, s11, 0
	s_add_u32 s12, s12, 0x8000
	s_addc_u32 s13, s13, 0
	s_add_u32 s14, s14, 0x4000
	s_addc_u32 s15, s15, 0
	s_add_u32 s16, s16, 0x200
	s_addc_u32 s17, s17, 0
	global_load_dwordx4 v[38:41], v8, s[10:11]
	global_load_dwordx4 v[42:45], v9, s[10:11]
	global_load_dwordx2 v[46:47], v10, s[12:13]
	global_load_dwordx2 v[48:49], v10, s[12:13] offset:512
	global_load_dwordx2 v[50:51], v11, s[14:15]
	global_load_dwordx4 v[52:55], v12, s[16:17]
	s_add_u32 s10, s10, 0x4000
	s_addc_u32 s11, s11, 0
	s_add_u32 s12, s12, 0x8000
	s_addc_u32 s13, s13, 0
	s_add_u32 s14, s14, 0x4000
	s_addc_u32 s15, s15, 0
	s_add_u32 s16, s16, 0x200
	s_addc_u32 s17, s17, 0
	global_load_dwordx4 v[56:59], v8, s[10:11]
	global_load_dwordx4 v[60:63], v9, s[10:11]
	global_load_dwordx2 v[64:65], v10, s[12:13]
	global_load_dwordx2 v[66:67], v10, s[12:13] offset:512
	global_load_dwordx2 v[68:69], v11, s[14:15]
	global_load_dwordx4 v[70:73], v12, s[16:17]
	s_add_u32 s10, s10, 0x4000
	s_addc_u32 s11, s11, 0
	s_add_u32 s12, s12, 0x8000
	s_addc_u32 s13, s13, 0
	s_add_u32 s14, s14, 0x4000
	s_addc_u32 s15, s15, 0
	s_add_u32 s16, s16, 0x200
	s_addc_u32 s17, s17, 0
	global_load_dwordx4 v[74:77], v8, s[10:11]
	global_load_dwordx4 v[78:81], v9, s[10:11]
	global_load_dwordx2 v[82:83], v10, s[12:13]
	global_load_dwordx2 v[84:85], v10, s[12:13] offset:512
	global_load_dwordx2 v[86:87], v11, s[14:15]
	global_load_dwordx4 v[88:91], v12, s[16:17]
	s_add_u32 s10, s10, 0x4000
	s_addc_u32 s11, s11, 0
	s_add_u32 s12, s12, 0x8000
	s_addc_u32 s13, s13, 0
	s_add_u32 s14, s14, 0x4000
	s_addc_u32 s15, s15, 0
	s_add_u32 s16, s16, 0x200
	s_addc_u32 s17, s17, 0
	global_load_dwordx4 v[92:95], v8, s[10:11]
	global_load_dwordx4 v[96:99], v9, s[10:11]
	global_load_dwordx2 v[100:101], v10, s[12:13]
	global_load_dwordx2 v[102:103], v10, s[12:13] offset:512
	global_load_dwordx2 v[104:105], v11, s[14:15]
	global_load_dwordx4 v[106:109], v12, s[16:17]
	s_add_u32 s10, s10, 0x4000
	s_addc_u32 s11, s11, 0
	s_add_u32 s12, s12, 0x8000
	s_addc_u32 s13, s13, 0
	s_add_u32 s14, s14, 0x4000
	s_addc_u32 s15, s15, 0
	s_add_u32 s16, s16, 0x200
	s_addc_u32 s17, s17, 0
	global_load_dwordx4 v[110:113], v8, s[10:11]
	global_load_dwordx4 v[114:117], v9, s[10:11]
	global_load_dwordx2 v[118:119], v10, s[12:13]
	global_load_dwordx2 v[120:121], v10, s[12:13] offset:512
	global_load_dwordx2 v[122:123], v11, s[14:15]
	global_load_dwordx4 v[124:127], v12, s[16:17]
	s_add_u32 s10, s10, 0x4000
	s_addc_u32 s11, s11, 0
	s_add_u32 s12, s12, 0x8000
	s_addc_u32 s13, s13, 0
	s_add_u32 s14, s14, 0x4000
	s_addc_u32 s15, s15, 0
	s_add_u32 s16, s16, 0x200
	s_addc_u32 s17, s17, 0
	s_mov_b32 s22, 0
	s_waitcnt vmcnt(0)
.Ls2_loop:
	s_cmp_lt_u32 s22, 64
	s_cbranch_scc0 .Ls2_done
	s_waitcnt vmcnt(50)
	ds_write_b128 v15, v[20:23] offset:0
	ds_write_b128 v15, v[24:27] offset:8704
	v_cvt_pk_bf16_f32 v232, v0, v1
	v_cvt_pk_bf16_f32 v233, v2, v3
	v_cvt_pk_bf16_f32 v234, v4, v5
	v_cvt_pk_bf16_f32 v235, v6, v7
	ds_write_b64 v16, v[232:233] offset:0
	ds_write_b64 v16, v[234:235] offset:4352
	v_lshlrev_b32_e32 v236, 16, v28
	v_and_b32_e32 v237, 0xffff0000, v28
	v_lshlrev_b32_e32 v238, 16, v29
	v_and_b32_e32 v239, 0xffff0000, v29
	v_lshlrev_b32_e32 v240, 16, v30
	v_and_b32_e32 v241, 0xffff0000, v30
	v_lshlrev_b32_e32 v242, 16, v31
	v_and_b32_e32 v243, 0xffff0000, v31
	v_pk_fma_f32 v[0:1], v[0:1], v[34:35], v[236:237]
	v_pk_fma_f32 v[2:3], v[2:3], v[36:37], v[238:239]
	v_pk_fma_f32 v[4:5], v[4:5], v[34:35], v[240:241]
	v_pk_fma_f32 v[6:7], v[6:7], v[36:37], v[242:243]
	s_waitcnt lgkmcnt(0)
	s_barrier
	ds_read_b128 v[184:187], v17 offset:0
	ds_read_b128 v[200:203], v18 offset:0
	ds_read_b128 v[188:191], v17 offset:64
	ds_read_b128 v[204:207], v18 offset:64
	ds_read_b128 v[192:195], v17 offset:128
	ds_read_b128 v[208:211], v18 offset:128
	ds_read_b128 v[196:199], v17 offset:192
	ds_read_b128 v[212:215], v18 offset:192
	v_lshlrev_b32_e32 v180, 16, v32
	v_and_b32_e32 v181, 0xffff0000, v32
	v_lshlrev_b32_e32 v182, 16, v33
	v_and_b32_e32 v183, 0xffff0000, v33
	s_waitcnt lgkmcnt(6)
	v_mfma_f32_16x16x32_bf16 v[164:167], v[184:187], v[200:203], 0
	s_waitcnt lgkmcnt(4)
	v_mfma_f32_16x16x32_bf16 v[164:167], v[188:191], v[204:207], v[164:167]
	s_waitcnt lgkmcnt(2)
	v_mfma_f32_16x16x32_bf16 v[164:167], v[192:195], v[208:211], v[164:167]
	s_waitcnt lgkmcnt(0)
	v_mfma_f32_16x16x32_bf16 v[164:167], v[196:199], v[212:215], v[164:167]
	s_nop 7
	s_nop 1
	v_add_f32_e32 v180, v164, v180
	v_add_f32_e32 v181, v165, v181
	v_add_f32_e32 v182, v166, v182
	v_add_f32_e32 v183, v167, v183
	v_cvt_pk_bf16_f32 v180, v180, s0
	v_cvt_pk_bf16_f32 v181, v181, s0
	v_cvt_pk_bf16_f32 v182, v182, s0
	v_cvt_pk_bf16_f32 v183, v183, s0
	global_store_short v13, v180, s[18:19]
	global_store_short v13, v181, s[18:19] offset:2048
	global_store_short v14, v182, s[18:19]
	global_store_short v14, v183, s[18:19] offset:2048
	global_load_dwordx4 v[20:23], v8, s[10:11]
	global_load_dwordx4 v[24:27], v9, s[10:11]
	global_load_dwordx2 v[28:29], v10, s[12:13]
	global_load_dwordx2 v[30:31], v10, s[12:13] offset:512
	global_load_dwordx2 v[32:33], v11, s[14:15]
	global_load_dwordx4 v[34:37], v12, s[16:17]
	s_add_u32 s18, s18, 0x20000
	s_addc_u32 s19, s19, 0
	s_cmp_lt_u32 s22, 57
	s_cbranch_scc0 .Ls2_na_l0
	s_add_u32 s10, s10, 0x4000
	s_addc_u32 s11, s11, 0
	s_add_u32 s12, s12, 0x8000
	s_addc_u32 s13, s13, 0
	s_add_u32 s14, s14, 0x4000
	s_addc_u32 s15, s15, 0
	s_add_u32 s16, s16, 0x200
	s_addc_u32 s17, s17, 0
.Ls2_na_l0:
	s_add_u32 s22, s22, 1
	s_cmp_lt_u32 s22, 64
	s_cbranch_scc0 .Ls2_done
	s_waitcnt vmcnt(50)
	ds_write_b128 v15, v[38:41] offset:26112
	ds_write_b128 v15, v[42:45] offset:34816
	v_cvt_pk_bf16_f32 v232, v0, v1
	v_cvt_pk_bf16_f32 v233, v2, v3
	v_cvt_pk_bf16_f32 v234, v4, v5
	v_cvt_pk_bf16_f32 v235, v6, v7
	ds_write_b64 v16, v[232:233] offset:26112
	ds_write_b64 v16, v[234:235] offset:30464
	v_lshlrev_b32_e32 v236, 16, v46
	v_and_b32_e32 v237, 0xffff0000, v46
	v_lshlrev_b32_e32 v238, 16, v47
	v_and_b32_e32 v239, 0xffff0000, v47
	v_lshlrev_b32_e32 v240, 16, v48
	v_and_b32_e32 v241, 0xffff0000, v48
	v_lshlrev_b32_e32 v242, 16, v49
	v_and_b32_e32 v243, 0xffff0000, v49
	v_pk_fma_f32 v[0:1], v[0:1], v[52:53], v[236:237]
	v_pk_fma_f32 v[2:3], v[2:3], v[54:55], v[238:239]
	v_pk_fma_f32 v[4:5], v[4:5], v[52:53], v[240:241]
	v_pk_fma_f32 v[6:7], v[6:7], v[54:55], v[242:243]
	s_waitcnt lgkmcnt(0)
	s_barrier
	ds_read_b128 v[184:187], v17 offset:26112
	ds_read_b128 v[200:203], v18 offset:26112
	ds_read_b128 v[188:191], v17 offset:26176
	ds_read_b128 v[204:207], v18 offset:26176
	ds_read_b128 v[192:195], v17 offset:26240
	ds_read_b128 v[208:211], v18 offset:26240
	ds_read_b128 v[196:199], v17 offset:26304
	ds_read_b128 v[212:215], v18 offset:26304
	v_lshlrev_b32_e32 v180, 16, v50
	v_and_b32_e32 v181, 0xffff0000, v50
	v_lshlrev_b32_e32 v182, 16, v51
	v_and_b32_e32 v183, 0xffff0000, v51
	s_waitcnt lgkmcnt(6)
	v_mfma_f32_16x16x32_bf16 v[164:167], v[184:187], v[200:203], 0
	s_waitcnt lgkmcnt(4)
	v_mfma_f32_16x16x32_bf16 v[164:167], v[188:191], v[204:207], v[164:167]
	s_waitcnt lgkmcnt(2)
	v_mfma_f32_16x16x32_bf16 v[164:167], v[192:195], v[208:211], v[164:167]
	s_waitcnt lgkmcnt(0)
	v_mfma_f32_16x16x32_bf16 v[164:167], v[196:199], v[212:215], v[164:167]
	s_nop 7
	s_nop 1
	v_add_f32_e32 v180, v164, v180
	v_add_f32_e32 v181, v165, v181
	v_add_f32_e32 v182, v166, v182
	v_add_f32_e32 v183, v167, v183
	v_cvt_pk_bf16_f32 v180, v180, s0
	v_cvt_pk_bf16_f32 v181, v181, s0
	v_cvt_pk_bf16_f32 v182, v182, s0
	v_cvt_pk_bf16_f32 v183, v183, s0
	global_store_short v13, v180, s[18:19]
	global_store_short v13, v181, s[18:19] offset:2048
	global_store_short v14, v182, s[18:19]
	global_store_short v14, v183, s[18:19] offset:2048
	global_load_dwordx4 v[38:41], v8, s[10:11]
	global_load_dwordx4 v[42:45], v9, s[10:11]
	global_load_dwordx2 v[46:47], v10, s[12:13]
	global_load_dwordx2 v[48:49], v10, s[12:13] offset:512
	global_load_dwordx2 v[50:51], v11, s[14:15]
	global_load_dwordx4 v[52:55], v12, s[16:17]
	s_add_u32 s18, s18, 0x20000
	s_addc_u32 s19, s19, 0
	s_cmp_lt_u32 s22, 57
	s_cbranch_scc0 .Ls2_na_l1
	s_add_u32 s10, s10, 0x4000
	s_addc_u32 s11, s11, 0
	s_add_u32 s12, s12, 0x8000
	s_addc_u32 s13, s13, 0
	s_add_u32 s14, s14, 0x4000
	s_addc_u32 s15, s15, 0
	s_add_u32 s16, s16, 0x200
	s_addc_u32 s17, s17, 0
.Ls2_na_l1:
	s_add_u32 s22, s22, 1
	s_cmp_lt_u32 s22, 64
	s_cbranch_scc0 .Ls2_done
	s_waitcnt vmcnt(50)
	ds_write_b128 v15, v[56:59] offset:0
	ds_write_b128 v15, v[60:63] offset:8704
	v_cvt_pk_bf16_f32 v232, v0, v1
	v_cvt_pk_bf16_f32 v233, v2, v3
	v_cvt_pk_bf16_f32 v234, v4, v5
	v_cvt_pk_bf16_f32 v235, v6, v7
	ds_write_b64 v16, v[232:233] offset:0
	ds_write_b64 v16, v[234:235] offset:4352
	v_lshlrev_b32_e32 v236, 16, v64
	v_and_b32_e32 v237, 0xffff0000, v64
	v_lshlrev_b32_e32 v238, 16, v65
	v_and_b32_e32 v239, 0xffff0000, v65
	v_lshlrev_b32_e32 v240, 16, v66
	v_and_b32_e32 v241, 0xffff0000, v66
	v_lshlrev_b32_e32 v242, 16, v67
	v_and_b32_e32 v243, 0xffff0000, v67
	v_pk_fma_f32 v[0:1], v[0:1], v[70:71], v[236:237]
	v_pk_fma_f32 v[2:3], v[2:3], v[72:73], v[238:239]
	v_pk_fma_f32 v[4:5], v[4:5], v[70:71], v[240:241]
	v_pk_fma_f32 v[6:7], v[6:7], v[72:73], v[242:243]
	s_waitcnt lgkmcnt(0)
	s_barrier
	ds_read_b128 v[184:187], v17 offset:0
	ds_read_b128 v[200:203], v18 offset:0
	ds_read_b128 v[188:191], v17 offset:64
	ds_read_b128 v[204:207], v18 offset:64
	ds_read_b128 v[192:195], v17 offset:128
	ds_read_b128 v[208:211], v18 offset:128
	ds_read_b128 v[196:199], v17 offset:192
	ds_read_b128 v[212:215], v18 offset:192
	v_lshlrev_b32_e32 v180, 16, v68
	v_and_b32_e32 v181, 0xffff0000, v68
	v_lshlrev_b32_e32 v182, 16, v69
	v_and_b32_e32 v183, 0xffff0000, v69
	s_waitcnt lgkmcnt(6)
	v_mfma_f32_16x16x32_bf16 v[164:167], v[184:187], v[200:203], 0
	s_waitcnt lgkmcnt(4)
	v_mfma_f32_16x16x32_bf16 v[164:167], v[188:191], v[204:207], v[164:167]
	s_waitcnt lgkmcnt(2)
	v_mfma_f32_16x16x32_bf16 v[164:167], v[192:195], v[208:211], v[164:167]
	s_waitcnt lgkmcnt(0)
	v_mfma_f32_16x16x32_bf16 v[164:167], v[196:199], v[212:215], v[164:167]
	s_nop 7
	s_nop 1
	v_add_f32_e32 v180, v164, v180
	v_add_f32_e32 v181, v165, v181
	v_add_f32_e32 v182, v166, v182
	v_add_f32_e32 v183, v167, v183
	v_cvt_pk_bf16_f32 v180, v180, s0
	v_cvt_pk_bf16_f32 v181, v181, s0
	v_cvt_pk_bf16_f32 v182, v182, s0
	v_cvt_pk_bf16_f32 v183, v183, s0
	global_store_short v13, v180, s[18:19]
	global_store_short v13, v181, s[18:19] offset:2048
	global_store_short v14, v182, s[18:19]
	global_store_short v14, v183, s[18:19] offset:2048
	global_load_dwordx4 v[56:59], v8, s[10:11]
	global_load_dwordx4 v[60:63], v9, s[10:11]
	global_load_dwordx2 v[64:65], v10, s[12:13]
	global_load_dwordx2 v[66:67], v10, s[12:13] offset:512
	global_load_dwordx2 v[68:69], v11, s[14:15]
	global_load_dwordx4 v[70:73], v12, s[16:17]
	s_add_u32 s18, s18, 0x20000
	s_addc_u32 s19, s19, 0
	s_cmp_lt_u32 s22, 57
	s_cbranch_scc0 .Ls2_na_l2
	s_add_u32 s10, s10, 0x4000
	s_addc_u32 s11, s11, 0
	s_add_u32 s12, s12, 0x8000
	s_addc_u32 s13, s13, 0
	s_add_u32 s14, s14, 0x4000
	s_addc_u32 s15, s15, 0
	s_add_u32 s16, s16, 0x200
	s_addc_u32 s17, s17, 0
.Ls2_na_l2:
	s_add_u32 s22, s22, 1
	s_cmp_lt_u32 s22, 64
	s_cbranch_scc0 .Ls2_done
	s_waitcnt vmcnt(50)
	ds_write_b128 v15, v[74:77] offset:26112
	ds_write_b128 v15, v[78:81] offset:34816
	v_cvt_pk_bf16_f32 v232, v0, v1
	v_cvt_pk_bf16_f32 v233, v2, v3
	v_cvt_pk_bf16_f32 v234, v4, v5
	v_cvt_pk_bf16_f32 v235, v6, v7
	ds_write_b64 v16, v[232:233] offset:26112
	ds_write_b64 v16, v[234:235] offset:30464
	v_lshlrev_b32_e32 v236, 16, v82
	v_and_b32_e32 v237, 0xffff0000, v82
	v_lshlrev_b32_e32 v238, 16, v83
	v_and_b32_e32 v239, 0xffff0000, v83
	v_lshlrev_b32_e32 v240, 16, v84
	v_and_b32_e32 v241, 0xffff0000, v84
	v_lshlrev_b32_e32 v242, 16, v85
	v_and_b32_e32 v243, 0xffff0000, v85
	v_pk_fma_f32 v[0:1], v[0:1], v[88:89], v[236:237]
	v_pk_fma_f32 v[2:3], v[2:3], v[90:91], v[238:239]
	v_pk_fma_f32 v[4:5], v[4:5], v[88:89], v[240:241]
	v_pk_fma_f32 v[6:7], v[6:7], v[90:91], v[242:243]
	s_waitcnt lgkmcnt(0)
	s_barrier
	ds_read_b128 v[184:187], v17 offset:26112
	ds_read_b128 v[200:203], v18 offset:26112
	ds_read_b128 v[188:191], v17 offset:26176
	ds_read_b128 v[204:207], v18 offset:26176
	ds_read_b128 v[192:195], v17 offset:26240
	ds_read_b128 v[208:211], v18 offset:26240
	ds_read_b128 v[196:199], v17 offset:26304
	ds_read_b128 v[212:215], v18 offset:26304
	v_lshlrev_b32_e32 v180, 16, v86
	v_and_b32_e32 v181, 0xffff0000, v86
	v_lshlrev_b32_e32 v182, 16, v87
	v_and_b32_e32 v183, 0xffff0000, v87
	s_waitcnt lgkmcnt(6)
	v_mfma_f32_16x16x32_bf16 v[164:167], v[184:187], v[200:203], 0
	s_waitcnt lgkmcnt(4)
	v_mfma_f32_16x16x32_bf16 v[164:167], v[188:191], v[204:207], v[164:167]
	s_waitcnt lgkmcnt(2)
	v_mfma_f32_16x16x32_bf16 v[164:167], v[192:195], v[208:211], v[164:167]
	s_waitcnt lgkmcnt(0)
	v_mfma_f32_16x16x32_bf16 v[164:167], v[196:199], v[212:215], v[164:167]
	s_nop 7
	s_nop 1
	v_add_f32_e32 v180, v164, v180
	v_add_f32_e32 v181, v165, v181
	v_add_f32_e32 v182, v166, v182
	v_add_f32_e32 v183, v167, v183
	v_cvt_pk_bf16_f32 v180, v180, s0
	v_cvt_pk_bf16_f32 v181, v181, s0
	v_cvt_pk_bf16_f32 v182, v182, s0
	v_cvt_pk_bf16_f32 v183, v183, s0
	global_store_short v13, v180, s[18:19]
	global_store_short v13, v181, s[18:19] offset:2048
	global_store_short v14, v182, s[18:19]
	global_store_short v14, v183, s[18:19] offset:2048
	global_load_dwordx4 v[74:77], v8, s[10:11]
	global_load_dwordx4 v[78:81], v9, s[10:11]
	global_load_dwordx2 v[82:83], v10, s[12:13]
	global_load_dwordx2 v[84:85], v10, s[12:13] offset:512
	global_load_dwordx2 v[86:87], v11, s[14:15]
	global_load_dwordx4 v[88:91], v12, s[16:17]
	s_add_u32 s18, s18, 0x20000
	s_addc_u32 s19, s19, 0
	s_cmp_lt_u32 s22, 57
	s_cbranch_scc0 .Ls2_na_l3
	s_add_u32 s10, s10, 0x4000
	s_addc_u32 s11, s11, 0
	s_add_u32 s12, s12, 0x8000
	s_addc_u32 s13, s13, 0
	s_add_u32 s14, s14, 0x4000
	s_addc_u32 s15, s15, 0
	s_add_u32 s16, s16, 0x200
	s_addc_u32 s17, s17, 0
.Ls2_na_l3:
	s_add_u32 s22, s22, 1
	s_cmp_lt_u32 s22, 64
	s_cbranch_scc0 .Ls2_done
	s_waitcnt vmcnt(50)
	ds_write_b128 v15, v[92:95] offset:0
	ds_write_b128 v15, v[96:99] offset:8704
	v_cvt_pk_bf16_f32 v232, v0, v1
	v_cvt_pk_bf16_f32 v233, v2, v3
	v_cvt_pk_bf16_f32 v234, v4, v5
	v_cvt_pk_bf16_f32 v235, v6, v7
	ds_write_b64 v16, v[232:233] offset:0
	ds_write_b64 v16, v[234:235] offset:4352
	v_lshlrev_b32_e32 v236, 16, v100
	v_and_b32_e32 v237, 0xffff0000, v100
	v_lshlrev_b32_e32 v238, 16, v101
	v_and_b32_e32 v239, 0xffff0000, v101
	v_lshlrev_b32_e32 v240, 16, v102
	v_and_b32_e32 v241, 0xffff0000, v102
	v_lshlrev_b32_e32 v242, 16, v103
	v_and_b32_e32 v243, 0xffff0000, v103
	v_pk_fma_f32 v[0:1], v[0:1], v[106:107], v[236:237]
	v_pk_fma_f32 v[2:3], v[2:3], v[108:109], v[238:239]
	v_pk_fma_f32 v[4:5], v[4:5], v[106:107], v[240:241]
	v_pk_fma_f32 v[6:7], v[6:7], v[108:109], v[242:243]
	s_waitcnt lgkmcnt(0)
	s_barrier
	ds_read_b128 v[184:187], v17 offset:0
	ds_read_b128 v[200:203], v18 offset:0
	ds_read_b128 v[188:191], v17 offset:64
	ds_read_b128 v[204:207], v18 offset:64
	ds_read_b128 v[192:195], v17 offset:128
	ds_read_b128 v[208:211], v18 offset:128
	ds_read_b128 v[196:199], v17 offset:192
	ds_read_b128 v[212:215], v18 offset:192
	v_lshlrev_b32_e32 v180, 16, v104
	v_and_b32_e32 v181, 0xffff0000, v104
	v_lshlrev_b32_e32 v182, 16, v105
	v_and_b32_e32 v183, 0xffff0000, v105
	s_waitcnt lgkmcnt(6)
	v_mfma_f32_16x16x32_bf16 v[164:167], v[184:187], v[200:203], 0
	s_waitcnt lgkmcnt(4)
	v_mfma_f32_16x16x32_bf16 v[164:167], v[188:191], v[204:207], v[164:167]
	s_waitcnt lgkmcnt(2)
	v_mfma_f32_16x16x32_bf16 v[164:167], v[192:195], v[208:211], v[164:167]
	s_waitcnt lgkmcnt(0)
	v_mfma_f32_16x16x32_bf16 v[164:167], v[196:199], v[212:215], v[164:167]
	s_nop 7
	s_nop 1
	v_add_f32_e32 v180, v164, v180
	v_add_f32_e32 v181, v165, v181
	v_add_f32_e32 v182, v166, v182
	v_add_f32_e32 v183, v167, v183
	v_cvt_pk_bf16_f32 v180, v180, s0
	v_cvt_pk_bf16_f32 v181, v181, s0
	v_cvt_pk_bf16_f32 v182, v182, s0
	v_cvt_pk_bf16_f32 v183, v183, s0
	global_store_short v13, v180, s[18:19]
	global_store_short v13, v181, s[18:19] offset:2048
	global_store_short v14, v182, s[18:19]
	global_store_short v14, v183, s[18:19] offset:2048
	global_load_dwordx4 v[92:95], v8, s[10:11]
	global_load_dwordx4 v[96:99], v9, s[10:11]
	global_load_dwordx2 v[100:101], v10, s[12:13]
	global_load_dwordx2 v[102:103], v10, s[12:13] offset:512
	global_load_dwordx2 v[104:105], v11, s[14:15]
	global_load_dwordx4 v[106:109], v12, s[16:17]
	s_add_u32 s18, s18, 0x20000
	s_addc_u32 s19, s19, 0
	s_cmp_lt_u32 s22, 57
	s_cbranch_scc0 .Ls2_na_l4
	s_add_u32 s10, s10, 0x4000
	s_addc_u32 s11, s11, 0
	s_add_u32 s12, s12, 0x8000
	s_addc_u32 s13, s13, 0
	s_add_u32 s14, s14, 0x4000
	s_addc_u32 s15, s15, 0
	s_add_u32 s16, s16, 0x200
	s_addc_u32 s17, s17, 0
.Ls2_na_l4:
	s_add_u32 s22, s22, 1
	s_cmp_lt_u32 s22, 64
	s_cbranch_scc0 .Ls2_done
	s_waitcnt vmcnt(50)
	ds_write_b128 v15, v[110:113] offset:26112
	ds_write_b128 v15, v[114:117] offset:34816
	v_cvt_pk_bf16_f32 v232, v0, v1
	v_cvt_pk_bf16_f32 v233, v2, v3
	v_cvt_pk_bf16_f32 v234, v4, v5
	v_cvt_pk_bf16_f32 v235, v6, v7
	ds_write_b64 v16, v[232:233] offset:26112
	ds_write_b64 v16, v[234:235] offset:30464
	v_lshlrev_b32_e32 v236, 16, v118
	v_and_b32_e32 v237, 0xffff0000, v118
	v_lshlrev_b32_e32 v238, 16, v119
	v_and_b32_e32 v239, 0xffff0000, v119
	v_lshlrev_b32_e32 v240, 16, v120
	v_and_b32_e32 v241, 0xffff0000, v120
	v_lshlrev_b32_e32 v242, 16, v121
	v_and_b32_e32 v243, 0xffff0000, v121
	v_pk_fma_f32 v[0:1], v[0:1], v[124:125], v[236:237]
	v_pk_fma_f32 v[2:3], v[2:3], v[126:127], v[238:239]
	v_pk_fma_f32 v[4:5], v[4:5], v[124:125], v[240:241]
	v_pk_fma_f32 v[6:7], v[6:7], v[126:127], v[242:243]
	s_waitcnt lgkmcnt(0)
	s_barrier
	ds_read_b128 v[184:187], v17 offset:26112
	ds_read_b128 v[200:203], v18 offset:26112
	ds_read_b128 v[188:191], v17 offset:26176
	ds_read_b128 v[204:207], v18 offset:26176
	ds_read_b128 v[192:195], v17 offset:26240
	ds_read_b128 v[208:211], v18 offset:26240
	ds_read_b128 v[196:199], v17 offset:26304
	ds_read_b128 v[212:215], v18 offset:26304
	v_lshlrev_b32_e32 v180, 16, v122
	v_and_b32_e32 v181, 0xffff0000, v122
	v_lshlrev_b32_e32 v182, 16, v123
	v_and_b32_e32 v183, 0xffff0000, v123
	s_waitcnt lgkmcnt(6)
	v_mfma_f32_16x16x32_bf16 v[164:167], v[184:187], v[200:203], 0
	s_waitcnt lgkmcnt(4)
	v_mfma_f32_16x16x32_bf16 v[164:167], v[188:191], v[204:207], v[164:167]
	s_waitcnt lgkmcnt(2)
	v_mfma_f32_16x16x32_bf16 v[164:167], v[192:195], v[208:211], v[164:167]
	s_waitcnt lgkmcnt(0)
	v_mfma_f32_16x16x32_bf16 v[164:167], v[196:199], v[212:215], v[164:167]
	s_nop 7
	s_nop 1
	v_add_f32_e32 v180, v164, v180
	v_add_f32_e32 v181, v165, v181
	v_add_f32_e32 v182, v166, v182
	v_add_f32_e32 v183, v167, v183
	v_cvt_pk_bf16_f32 v180, v180, s0
	v_cvt_pk_bf16_f32 v181, v181, s0
	v_cvt_pk_bf16_f32 v182, v182, s0
	v_cvt_pk_bf16_f32 v183, v183, s0
	global_store_short v13, v180, s[18:19]
	global_store_short v13, v181, s[18:19] offset:2048
	global_store_short v14, v182, s[18:19]
	global_store_short v14, v183, s[18:19] offset:2048
	global_load_dwordx4 v[110:113], v8, s[10:11]
	global_load_dwordx4 v[114:117], v9, s[10:11]
	global_load_dwordx2 v[118:119], v10, s[12:13]
	global_load_dwordx2 v[120:121], v10, s[12:13] offset:512
	global_load_dwordx2 v[122:123], v11, s[14:15]
	global_load_dwordx4 v[124:127], v12, s[16:17]
	s_add_u32 s18, s18, 0x20000
	s_addc_u32 s19, s19, 0
	s_cmp_lt_u32 s22, 57
	s_cbranch_scc0 .Ls2_na_l5
	s_add_u32 s10, s10, 0x4000
	s_addc_u32 s11, s11, 0
	s_add_u32 s12, s12, 0x8000
	s_addc_u32 s13, s13, 0
	s_add_u32 s14, s14, 0x4000
	s_addc_u32 s15, s15, 0
	s_add_u32 s16, s16, 0x200
	s_addc_u32 s17, s17, 0
.Ls2_na_l5:
	s_add_u32 s22, s22, 1
	s_branch .Ls2_loop
.Ls2_done:
	s_waitcnt vmcnt(0)
	s_branch .LBB0_549
